# GEMM K loops: the closing barrier of the last iteration is skipped (it only paired the leading half's rejoin with the other half's last compute segment); the leading half's barrier behind the loop tak
# baseline (speedup 1.0000x reference)
.LBB0_32:
	s_add_u32 s12, s10, 0x100
	s_addc_u32 s13, s11, 0
	s_cmpk_eq_i32 s42, 0x52
	s_cselect_b32 s17, s1, s13
	s_cselect_b32 s16, s0, s12
	s_cselect_b32 s15, s9, s41
	s_cselect_b32 s14, s8, s40
	ds_read_b128 v[130:133], v204
	ds_read_b128 v[134:137], v204 offset:1024
	ds_read_b128 v[138:141], v204 offset:2048
	ds_read_b128 v[142:145], v204 offset:3072
	ds_read_b128 v[146:149], v205
	ds_read_b128 v[150:153], v205 offset:1024
	ds_read_b128 v[154:157], v205 offset:2048
	ds_read_b128 v[158:161], v205 offset:3072
	ds_read_b128 v[162:165], v208
	ds_read_b128 v[166:169], v208 offset:1024
	ds_read_b128 v[170:173], v208 offset:2048
	ds_read_b128 v[184:187], v208 offset:3072
	ds_read_b128 v[188:191], v208 offset:4096
	s_add_i32 m0, s23, 0xc000
	ds_read_b128 v[192:195], v208 offset:5120
	global_load_lds_dwordx4 v180, s[10:11]
	s_add_i32 m0, s23, 0xe000
	ds_read_b128 v[196:199], v208 offset:6144
	global_load_lds_dwordx4 v182, s[10:11]
	ds_read_b128 v[200:203], v208 offset:7168
	s_waitcnt vmcnt(8) lgkmcnt(0)
	s_barrier
	v_mfma_f32_16x16x32_bf16 v[126:129], v[130:133], v[162:165], v[126:129]
	v_mfma_f32_16x16x32_bf16 v[94:97], v[138:141], v[162:165], v[94:97]
	v_mfma_f32_16x16x32_bf16 v[122:125], v[130:133], v[170:173], v[122:125]
	v_mfma_f32_16x16x32_bf16 v[90:93], v[138:141], v[170:173], v[90:93]
	v_mfma_f32_16x16x32_bf16 v[118:121], v[130:133], v[188:191], v[118:121]
	v_mfma_f32_16x16x32_bf16 v[86:89], v[138:141], v[188:191], v[86:89]
	v_mfma_f32_16x16x32_bf16 v[114:117], v[130:133], v[196:199], v[114:117]
	v_mfma_f32_16x16x32_bf16 v[82:85], v[138:141], v[196:199], v[82:85]
	v_mfma_f32_16x16x32_bf16 v[126:129], v[134:137], v[166:169], v[126:129]
	v_mfma_f32_16x16x32_bf16 v[94:97], v[142:145], v[166:169], v[94:97]
	v_mfma_f32_16x16x32_bf16 v[122:125], v[134:137], v[184:187], v[122:125]
	v_mfma_f32_16x16x32_bf16 v[90:93], v[142:145], v[184:187], v[90:93]
	v_mfma_f32_16x16x32_bf16 v[118:121], v[134:137], v[192:195], v[118:121]
	v_mfma_f32_16x16x32_bf16 v[86:89], v[142:145], v[192:195], v[86:89]
	v_mfma_f32_16x16x32_bf16 v[114:117], v[134:137], v[200:203], v[114:117]
	v_mfma_f32_16x16x32_bf16 v[82:85], v[142:145], v[200:203], v[82:85]
	v_mfma_f32_16x16x32_bf16 v[66:69], v[146:149], v[162:165], v[66:69]
	v_mfma_f32_16x16x32_bf16 v[42:45], v[154:157], v[162:165], v[42:45]
	v_mfma_f32_16x16x32_bf16 v[58:61], v[146:149], v[170:173], v[58:61]
	v_mfma_f32_16x16x32_bf16 v[30:33], v[154:157], v[170:173], v[30:33]
	v_mfma_f32_16x16x32_bf16 v[54:57], v[146:149], v[188:191], v[54:57]
	v_mfma_f32_16x16x32_bf16 v[22:25], v[154:157], v[188:191], v[22:25]
	v_mfma_f32_16x16x32_bf16 v[50:53], v[146:149], v[196:199], v[50:53]
	v_mfma_f32_16x16x32_bf16 v[18:21], v[154:157], v[196:199], v[18:21]
	v_mfma_f32_16x16x32_bf16 v[66:69], v[150:153], v[166:169], v[66:69]
	v_mfma_f32_16x16x32_bf16 v[42:45], v[158:161], v[166:169], v[42:45]
	v_mfma_f32_16x16x32_bf16 v[58:61], v[150:153], v[184:187], v[58:61]
	v_mfma_f32_16x16x32_bf16 v[30:33], v[158:161], v[184:187], v[30:33]
	v_mfma_f32_16x16x32_bf16 v[54:57], v[150:153], v[192:195], v[54:57]
	v_mfma_f32_16x16x32_bf16 v[22:25], v[158:161], v[192:195], v[22:25]
	v_mfma_f32_16x16x32_bf16 v[50:53], v[150:153], v[200:203], v[50:53]
	v_mfma_f32_16x16x32_bf16 v[18:21], v[158:161], v[200:203], v[18:21]
	s_barrier
	ds_read_b128 v[162:165], v208 offset:16384
	s_add_i32 m0, s22, 0x10000
	ds_read_b128 v[166:169], v208 offset:17408
	global_load_lds_dwordx4 v178, s[14:15]
	s_add_i32 m0, s22, 0x12000
	s_add_u32 s10, s14, 0x158000
	s_addc_u32 s11, s15, 0
	ds_read_b128 v[170:173], v208 offset:18432
	global_load_lds_dwordx4 v176, s[14:15]
	s_add_i32 m0, s22, 0x14000
	ds_read_b128 v[184:187], v208 offset:19456
	global_load_lds_dwordx4 v178, s[10:11]
	s_add_i32 m0, s22, 0x16000
	ds_read_b128 v[188:191], v208 offset:20480
	global_load_lds_dwordx4 v176, s[10:11]
	s_mov_b32 m0, s23
	ds_read_b128 v[192:195], v208 offset:21504
	global_load_lds_dwordx4 v178, s[16:17]
	s_mov_b32 m0, s24
	ds_read_b128 v[196:199], v208 offset:22528
	global_load_lds_dwordx4 v176, s[16:17]
	ds_read_b128 v[200:203], v208 offset:23552
	s_waitcnt vmcnt(8) lgkmcnt(0)
	s_barrier
	v_mfma_f32_16x16x32_bf16 v[110:113], v[130:133], v[162:165], v[110:113]
	v_mfma_f32_16x16x32_bf16 v[78:81], v[138:141], v[162:165], v[78:81]
	v_mfma_f32_16x16x32_bf16 v[106:109], v[130:133], v[170:173], v[106:109]
	v_mfma_f32_16x16x32_bf16 v[74:77], v[138:141], v[170:173], v[74:77]
	v_mfma_f32_16x16x32_bf16 v[102:105], v[130:133], v[188:191], v[102:105]
	v_mfma_f32_16x16x32_bf16 v[70:73], v[138:141], v[188:191], v[70:73]
	v_mfma_f32_16x16x32_bf16 v[98:101], v[130:133], v[196:199], v[98:101]
	v_mfma_f32_16x16x32_bf16 v[62:65], v[138:141], v[196:199], v[62:65]
	v_mfma_f32_16x16x32_bf16 v[110:113], v[134:137], v[166:169], v[110:113]
	v_mfma_f32_16x16x32_bf16 v[78:81], v[142:145], v[166:169], v[78:81]
	v_mfma_f32_16x16x32_bf16 v[106:109], v[134:137], v[184:187], v[106:109]
	v_mfma_f32_16x16x32_bf16 v[74:77], v[142:145], v[184:187], v[74:77]
	v_mfma_f32_16x16x32_bf16 v[102:105], v[134:137], v[192:195], v[102:105]
	v_mfma_f32_16x16x32_bf16 v[70:73], v[142:145], v[192:195], v[70:73]
	v_mfma_f32_16x16x32_bf16 v[98:101], v[134:137], v[200:203], v[98:101]
	v_mfma_f32_16x16x32_bf16 v[62:65], v[142:145], v[200:203], v[62:65]
	v_mfma_f32_16x16x32_bf16 v[46:49], v[146:149], v[162:165], v[46:49]
	v_mfma_f32_16x16x32_bf16 v[12:15], v[154:157], v[162:165], v[12:15]
	v_mfma_f32_16x16x32_bf16 v[38:41], v[146:149], v[170:173], v[38:41]
	v_mfma_f32_16x16x32_bf16 v[8:11], v[154:157], v[170:173], v[8:11]
	v_mfma_f32_16x16x32_bf16 v[34:37], v[146:149], v[188:191], v[34:37]
	v_mfma_f32_16x16x32_bf16 v[4:7], v[154:157], v[188:191], v[4:7]
	v_mfma_f32_16x16x32_bf16 v[26:29], v[146:149], v[196:199], v[26:29]
	v_mfma_f32_16x16x32_bf16 v[0:3], v[154:157], v[196:199], v[0:3]
	v_mfma_f32_16x16x32_bf16 v[46:49], v[150:153], v[166:169], v[46:49]
	v_mfma_f32_16x16x32_bf16 v[12:15], v[158:161], v[166:169], v[12:15]
	v_mfma_f32_16x16x32_bf16 v[38:41], v[150:153], v[184:187], v[38:41]
	v_mfma_f32_16x16x32_bf16 v[8:11], v[158:161], v[184:187], v[8:11]
	v_mfma_f32_16x16x32_bf16 v[34:37], v[150:153], v[192:195], v[34:37]
	v_mfma_f32_16x16x32_bf16 v[4:7], v[158:161], v[192:195], v[4:7]
	v_mfma_f32_16x16x32_bf16 v[26:29], v[150:153], v[200:203], v[26:29]
	v_mfma_f32_16x16x32_bf16 v[0:3], v[158:161], v[200:203], v[0:3]
	s_barrier
	s_add_u32 s100, s16, 0x158000
	s_addc_u32 s101, s17, 0
	ds_read_b128 v[130:133], v210
	ds_read_b128 v[134:137], v210 offset:1024
	ds_read_b128 v[138:141], v210 offset:2048
	ds_read_b128 v[142:145], v210 offset:3072
	ds_read_b128 v[146:149], v211
	ds_read_b128 v[150:153], v211 offset:1024
	ds_read_b128 v[154:157], v211 offset:2048
	ds_read_b128 v[158:161], v211 offset:3072
	ds_read_b128 v[162:165], v208 offset:32768
	ds_read_b128 v[166:169], v208 offset:33792
	ds_read_b128 v[170:173], v208 offset:34816
	ds_read_b128 v[184:187], v208 offset:35840
	ds_read_b128 v[188:191], v208 offset:36864
	s_mov_b32 m0, s25
	ds_read_b128 v[192:195], v208 offset:37888
	global_load_lds_dwordx4 v178, s[100:101]
	s_mov_b32 m0, s26
	ds_read_b128 v[196:199], v208 offset:38912
	global_load_lds_dwordx4 v176, s[100:101]
	ds_read_b128 v[200:203], v208 offset:39936
	s_waitcnt vmcnt(8) lgkmcnt(0)
	s_barrier
	v_mfma_f32_16x16x32_bf16 v[126:129], v[130:133], v[162:165], v[126:129]
	v_mfma_f32_16x16x32_bf16 v[94:97], v[138:141], v[162:165], v[94:97]
	v_mfma_f32_16x16x32_bf16 v[122:125], v[130:133], v[170:173], v[122:125]
	v_mfma_f32_16x16x32_bf16 v[90:93], v[138:141], v[170:173], v[90:93]
	v_mfma_f32_16x16x32_bf16 v[118:121], v[130:133], v[188:191], v[118:121]
	v_mfma_f32_16x16x32_bf16 v[86:89], v[138:141], v[188:191], v[86:89]
	v_mfma_f32_16x16x32_bf16 v[114:117], v[130:133], v[196:199], v[114:117]
	v_mfma_f32_16x16x32_bf16 v[82:85], v[138:141], v[196:199], v[82:85]
	v_mfma_f32_16x16x32_bf16 v[126:129], v[134:137], v[166:169], v[126:129]
	v_mfma_f32_16x16x32_bf16 v[94:97], v[142:145], v[166:169], v[94:97]
	v_mfma_f32_16x16x32_bf16 v[122:125], v[134:137], v[184:187], v[122:125]
	v_mfma_f32_16x16x32_bf16 v[90:93], v[142:145], v[184:187], v[90:93]
	v_mfma_f32_16x16x32_bf16 v[118:121], v[134:137], v[192:195], v[118:121]
	v_mfma_f32_16x16x32_bf16 v[86:89], v[142:145], v[192:195], v[86:89]
	v_mfma_f32_16x16x32_bf16 v[114:117], v[134:137], v[200:203], v[114:117]
	v_mfma_f32_16x16x32_bf16 v[82:85], v[142:145], v[200:203], v[82:85]
	v_mfma_f32_16x16x32_bf16 v[66:69], v[146:149], v[162:165], v[66:69]
	v_mfma_f32_16x16x32_bf16 v[42:45], v[154:157], v[162:165], v[42:45]
	v_mfma_f32_16x16x32_bf16 v[58:61], v[146:149], v[170:173], v[58:61]
	v_mfma_f32_16x16x32_bf16 v[30:33], v[154:157], v[170:173], v[30:33]
	v_mfma_f32_16x16x32_bf16 v[54:57], v[146:149], v[188:191], v[54:57]
	v_mfma_f32_16x16x32_bf16 v[22:25], v[154:157], v[188:191], v[22:25]
	v_mfma_f32_16x16x32_bf16 v[50:53], v[146:149], v[196:199], v[50:53]
	v_mfma_f32_16x16x32_bf16 v[18:21], v[154:157], v[196:199], v[18:21]
	v_mfma_f32_16x16x32_bf16 v[66:69], v[150:153], v[166:169], v[66:69]
	v_mfma_f32_16x16x32_bf16 v[42:45], v[158:161], v[166:169], v[42:45]
	v_mfma_f32_16x16x32_bf16 v[58:61], v[150:153], v[184:187], v[58:61]
	v_mfma_f32_16x16x32_bf16 v[30:33], v[158:161], v[184:187], v[30:33]
	v_mfma_f32_16x16x32_bf16 v[54:57], v[150:153], v[192:195], v[54:57]
	v_mfma_f32_16x16x32_bf16 v[22:25], v[158:161], v[192:195], v[22:25]
	v_mfma_f32_16x16x32_bf16 v[50:53], v[150:153], v[200:203], v[50:53]
	v_mfma_f32_16x16x32_bf16 v[18:21], v[158:161], v[200:203], v[18:21]
	s_barrier
	ds_read_b128 v[162:165], v208 offset:49152
	s_add_i32 m0, s22, 0x17f80
	ds_read_b128 v[166:169], v208 offset:50176
	global_load_lds_dwordx4 v178, s[14:15] offset:128
	s_add_i32 m0, s22, 0x19f80
	ds_read_b128 v[170:173], v208 offset:51200
	global_load_lds_dwordx4 v176, s[14:15] offset:128
	s_add_i32 m0, s22, 0x1bf80
	ds_read_b128 v[184:187], v208 offset:52224
	global_load_lds_dwordx4 v178, s[10:11] offset:128
	s_add_i32 m0, s22, 0x1df80
	ds_read_b128 v[188:191], v208 offset:53248
	global_load_lds_dwordx4 v176, s[10:11] offset:128
	s_add_i32 m0, s31, 0xffffff80
	ds_read_b128 v[192:195], v208 offset:54272
	global_load_lds_dwordx4 v178, s[16:17] offset:128
	s_add_i32 m0, s34, 0xffffff80
	ds_read_b128 v[196:199], v208 offset:55296
	global_load_lds_dwordx4 v176, s[16:17] offset:128
	ds_read_b128 v[200:203], v208 offset:56320
	s_waitcnt vmcnt(8) lgkmcnt(0)
	s_barrier
	v_mfma_f32_16x16x32_bf16 v[110:113], v[130:133], v[162:165], v[110:113]
	v_mfma_f32_16x16x32_bf16 v[78:81], v[138:141], v[162:165], v[78:81]
	v_mfma_f32_16x16x32_bf16 v[106:109], v[130:133], v[170:173], v[106:109]
	v_mfma_f32_16x16x32_bf16 v[74:77], v[138:141], v[170:173], v[74:77]
	v_mfma_f32_16x16x32_bf16 v[102:105], v[130:133], v[188:191], v[102:105]
	v_mfma_f32_16x16x32_bf16 v[70:73], v[138:141], v[188:191], v[70:73]
	v_mfma_f32_16x16x32_bf16 v[98:101], v[130:133], v[196:199], v[98:101]
	v_mfma_f32_16x16x32_bf16 v[62:65], v[138:141], v[196:199], v[62:65]
	v_mfma_f32_16x16x32_bf16 v[110:113], v[134:137], v[166:169], v[110:113]
	v_mfma_f32_16x16x32_bf16 v[78:81], v[142:145], v[166:169], v[78:81]
	v_mfma_f32_16x16x32_bf16 v[106:109], v[134:137], v[184:187], v[106:109]
	v_mfma_f32_16x16x32_bf16 v[74:77], v[142:145], v[184:187], v[74:77]
	v_mfma_f32_16x16x32_bf16 v[102:105], v[134:137], v[192:195], v[102:105]
	v_mfma_f32_16x16x32_bf16 v[70:73], v[142:145], v[192:195], v[70:73]
	v_mfma_f32_16x16x32_bf16 v[98:101], v[134:137], v[200:203], v[98:101]
	v_mfma_f32_16x16x32_bf16 v[62:65], v[142:145], v[200:203], v[62:65]
	v_mfma_f32_16x16x32_bf16 v[46:49], v[146:149], v[162:165], v[46:49]
	v_mfma_f32_16x16x32_bf16 v[12:15], v[154:157], v[162:165], v[12:15]
	v_mfma_f32_16x16x32_bf16 v[38:41], v[146:149], v[170:173], v[38:41]
	v_mfma_f32_16x16x32_bf16 v[8:11], v[154:157], v[170:173], v[8:11]
	v_mfma_f32_16x16x32_bf16 v[34:37], v[146:149], v[188:191], v[34:37]
	v_mfma_f32_16x16x32_bf16 v[4:7], v[154:157], v[188:191], v[4:7]
	v_mfma_f32_16x16x32_bf16 v[26:29], v[146:149], v[196:199], v[26:29]
	v_mfma_f32_16x16x32_bf16 v[0:3], v[154:157], v[196:199], v[0:3]
	v_mfma_f32_16x16x32_bf16 v[46:49], v[150:153], v[166:169], v[46:49]
	v_mfma_f32_16x16x32_bf16 v[12:15], v[158:161], v[166:169], v[12:15]
	v_mfma_f32_16x16x32_bf16 v[38:41], v[150:153], v[184:187], v[38:41]
	v_mfma_f32_16x16x32_bf16 v[8:11], v[158:161], v[184:187], v[8:11]
	v_mfma_f32_16x16x32_bf16 v[34:37], v[150:153], v[192:195], v[34:37]
	v_mfma_f32_16x16x32_bf16 v[4:7], v[158:161], v[192:195], v[4:7]
	v_mfma_f32_16x16x32_bf16 v[26:29], v[150:153], v[200:203], v[26:29]
	v_mfma_f32_16x16x32_bf16 v[0:3], v[158:161], v[200:203], v[0:3]
	s_cmpk_eq_i32 s42, 0x52
	s_cbranch_scc1 .Lxb_d2
	s_barrier
	s_add_i32 s42, s42, 2
	s_add_u32 s40, s40, 0x100
	s_addc_u32 s41, s41, 0
	s_mov_b64 s[10:11], s[12:13]
	s_branch .LBB0_32
.Lxb_d2:
	s_add_i32 s42, s42, 2
	s_add_u32 s40, s40, 0x100
	s_addc_u32 s41, s41, 0
	s_mov_b64 s[10:11], s[12:13]
	s_and_b64 vcc, exec, s[6:7]
	s_cbranch_vccz .LBB0_35
	s_barrier

.LBB0_68:
	s_add_u32 s8, s6, 0xfff80080
	s_addc_u32 s9, s7, -1
	s_cmp_eq_u32 s51, 28
	s_cselect_b32 s11, s21, s9
	s_cselect_b32 s10, s28, s8
	s_cselect_b32 s9, s19, s31
	s_cselect_b32 s8, s29, s30
	ds_read_b128 v[54:57], v214
	ds_read_b128 v[62:65], v214 offset:1024
	ds_read_b128 v[66:69], v214 offset:2048
	ds_read_b128 v[70:73], v214 offset:3072
	ds_read_b128 v[74:77], v215
	ds_read_b128 v[78:81], v215 offset:1024
	ds_read_b128 v[82:85], v215 offset:2048
	ds_read_b128 v[86:89], v215 offset:3072
	ds_read_b128 v[170:173], v192
	ds_read_b128 v[184:187], v192 offset:1024
	ds_read_b128 v[194:197], v192 offset:2048
	ds_read_b128 v[198:201], v192 offset:3072
	ds_read_b128 v[202:205], v192 offset:4096
	s_add_i32 m0, s41, 0xc000
	ds_read_b128 v[206:209], v192 offset:5120
	global_load_lds_dwordx4 v180, s[6:7]
	s_add_i32 m0, s41, 0xe000
	ds_read_b128 v[210:213], v192 offset:6144
	global_load_lds_dwordx4 v182, s[6:7]
	ds_read_b128 v[222:225], v192 offset:7168
	s_waitcnt vmcnt(8) lgkmcnt(0)
	s_barrier
	v_mfma_f32_16x16x32_bf16 v[150:153], v[54:57], v[170:173], v[150:153]
	v_mfma_f32_16x16x32_bf16 v[142:145], v[66:69], v[170:173], v[142:145]
	v_mfma_f32_16x16x32_bf16 v[134:137], v[54:57], v[194:197], v[134:137]
	v_mfma_f32_16x16x32_bf16 v[126:129], v[66:69], v[194:197], v[126:129]
	v_mfma_f32_16x16x32_bf16 v[118:121], v[54:57], v[202:205], v[118:121]
	v_mfma_f32_16x16x32_bf16 v[114:117], v[66:69], v[202:205], v[114:117]
	v_mfma_f32_16x16x32_bf16 v[110:113], v[54:57], v[210:213], v[110:113]
	v_mfma_f32_16x16x32_bf16 v[106:109], v[66:69], v[210:213], v[106:109]
	v_mfma_f32_16x16x32_bf16 v[150:153], v[62:65], v[184:187], v[150:153]
	v_mfma_f32_16x16x32_bf16 v[142:145], v[70:73], v[184:187], v[142:145]
	v_mfma_f32_16x16x32_bf16 v[134:137], v[62:65], v[198:201], v[134:137]
	v_mfma_f32_16x16x32_bf16 v[126:129], v[70:73], v[198:201], v[126:129]
	v_mfma_f32_16x16x32_bf16 v[118:121], v[62:65], v[206:209], v[118:121]
	v_mfma_f32_16x16x32_bf16 v[114:117], v[70:73], v[206:209], v[114:117]
	v_mfma_f32_16x16x32_bf16 v[110:113], v[62:65], v[222:225], v[110:113]
	v_mfma_f32_16x16x32_bf16 v[106:109], v[70:73], v[222:225], v[106:109]
	v_mfma_f32_16x16x32_bf16 v[158:161], v[74:77], v[170:173], v[158:161]
	v_mfma_f32_16x16x32_bf16 v[154:157], v[82:85], v[170:173], v[154:157]
	v_mfma_f32_16x16x32_bf16 v[146:149], v[74:77], v[194:197], v[146:149]
	v_mfma_f32_16x16x32_bf16 v[138:141], v[82:85], v[194:197], v[138:141]
	v_mfma_f32_16x16x32_bf16 v[130:133], v[74:77], v[202:205], v[130:133]
	v_mfma_f32_16x16x32_bf16 v[122:125], v[82:85], v[202:205], v[122:125]
	v_mfma_f32_16x16x32_bf16 v[102:105], v[74:77], v[210:213], v[102:105]
	v_mfma_f32_16x16x32_bf16 v[98:101], v[82:85], v[210:213], v[98:101]
	v_mfma_f32_16x16x32_bf16 v[158:161], v[78:81], v[184:187], v[158:161]
	v_mfma_f32_16x16x32_bf16 v[154:157], v[86:89], v[184:187], v[154:157]
	v_mfma_f32_16x16x32_bf16 v[146:149], v[78:81], v[198:201], v[146:149]
	v_mfma_f32_16x16x32_bf16 v[138:141], v[86:89], v[198:201], v[138:141]
	v_mfma_f32_16x16x32_bf16 v[130:133], v[78:81], v[206:209], v[130:133]
	v_mfma_f32_16x16x32_bf16 v[122:125], v[86:89], v[206:209], v[122:125]
	v_mfma_f32_16x16x32_bf16 v[102:105], v[78:81], v[222:225], v[102:105]
	v_mfma_f32_16x16x32_bf16 v[98:101], v[86:89], v[222:225], v[98:101]
	s_barrier
	ds_read_b128 v[170:173], v192 offset:16384
	s_add_i32 m0, s38, 0x10000
	ds_read_b128 v[184:187], v192 offset:17408
	global_load_lds_dwordx4 v166, s[8:9]
	s_add_i32 m0, s38, 0x12000
	s_add_u32 s52, s8, 0x80000
	s_addc_u32 s53, s9, 0
	ds_read_b128 v[194:197], v192 offset:18432
	global_load_lds_dwordx4 v162, s[8:9]
	s_add_i32 m0, s38, 0x14000
	ds_read_b128 v[198:201], v192 offset:19456
	global_load_lds_dwordx4 v166, s[52:53]
	s_add_i32 m0, s38, 0x16000
	ds_read_b128 v[202:205], v192 offset:20480
	global_load_lds_dwordx4 v162, s[52:53]
	s_mov_b32 m0, s41
	ds_read_b128 v[206:209], v192 offset:21504
	global_load_lds_dwordx4 v168, s[10:11]
	s_mov_b32 m0, s42
	ds_read_b128 v[210:213], v192 offset:22528
	global_load_lds_dwordx4 v164, s[10:11]
	ds_read_b128 v[222:225], v192 offset:23552
	s_waitcnt vmcnt(8) lgkmcnt(0)
	s_barrier
	v_mfma_f32_16x16x32_bf16 v[58:61], v[54:57], v[170:173], v[58:61]
	v_mfma_f32_16x16x32_bf16 v[46:49], v[66:69], v[170:173], v[46:49]
	v_mfma_f32_16x16x32_bf16 v[38:41], v[54:57], v[194:197], v[38:41]
	v_mfma_f32_16x16x32_bf16 v[30:33], v[66:69], v[194:197], v[30:33]
	v_mfma_f32_16x16x32_bf16 v[22:25], v[54:57], v[202:205], v[22:25]
	v_mfma_f32_16x16x32_bf16 v[18:21], v[66:69], v[202:205], v[18:21]
	v_mfma_f32_16x16x32_bf16 v[8:11], v[54:57], v[210:213], v[8:11]
	v_mfma_f32_16x16x32_bf16 v[12:15], v[66:69], v[210:213], v[12:15]
	v_mfma_f32_16x16x32_bf16 v[58:61], v[62:65], v[184:187], v[58:61]
	v_mfma_f32_16x16x32_bf16 v[46:49], v[70:73], v[184:187], v[46:49]
	v_mfma_f32_16x16x32_bf16 v[38:41], v[62:65], v[198:201], v[38:41]
	v_mfma_f32_16x16x32_bf16 v[30:33], v[70:73], v[198:201], v[30:33]
	v_mfma_f32_16x16x32_bf16 v[22:25], v[62:65], v[206:209], v[22:25]
	v_mfma_f32_16x16x32_bf16 v[18:21], v[70:73], v[206:209], v[18:21]
	v_mfma_f32_16x16x32_bf16 v[8:11], v[62:65], v[222:225], v[8:11]
	v_mfma_f32_16x16x32_bf16 v[12:15], v[70:73], v[222:225], v[12:15]
	v_mfma_f32_16x16x32_bf16 v[50:53], v[74:77], v[194:197], v[50:53]
	v_mfma_f32_16x16x32_bf16 v[42:45], v[82:85], v[194:197], v[42:45]
	v_mfma_f32_16x16x32_bf16 v[34:37], v[74:77], v[202:205], v[34:37]
	v_mfma_f32_16x16x32_bf16 v[26:29], v[82:85], v[202:205], v[26:29]
	v_mfma_f32_16x16x32_bf16 v[0:3], v[74:77], v[210:213], v[0:3]
	v_mfma_f32_16x16x32_bf16 v[4:7], v[82:85], v[210:213], v[4:7]
	v_mfma_f32_16x16x32_bf16 v[54:57], v[74:77], v[170:173], v[94:97]
	v_mfma_f32_16x16x32_bf16 v[62:65], v[82:85], v[170:173], v[90:93]
	v_mfma_f32_16x16x32_bf16 v[50:53], v[78:81], v[198:201], v[50:53]
	v_mfma_f32_16x16x32_bf16 v[42:45], v[86:89], v[198:201], v[42:45]
	v_mfma_f32_16x16x32_bf16 v[34:37], v[78:81], v[206:209], v[34:37]
	v_mfma_f32_16x16x32_bf16 v[26:29], v[86:89], v[206:209], v[26:29]
	v_mfma_f32_16x16x32_bf16 v[0:3], v[78:81], v[222:225], v[0:3]
	v_mfma_f32_16x16x32_bf16 v[4:7], v[86:89], v[222:225], v[4:7]
	v_mfma_f32_16x16x32_bf16 v[54:57], v[78:81], v[184:187], v[54:57]
	v_mfma_f32_16x16x32_bf16 v[62:65], v[86:89], v[184:187], v[62:65]
	s_barrier
	s_add_u32 s100, s10, 0x80000
	s_addc_u32 s101, s11, 0
	ds_read_b128 v[66:69], v234
	ds_read_b128 v[70:73], v234 offset:1024
	ds_read_b128 v[74:77], v234 offset:2048
	ds_read_b128 v[78:81], v234 offset:3072
	ds_read_b128 v[82:85], v235
	ds_read_b128 v[86:89], v235 offset:1024
	ds_read_b128 v[170:173], v235 offset:2048
	ds_read_b128 v[184:187], v235 offset:3072
	ds_read_b128 v[90:93], v192 offset:32768
	ds_read_b128 v[94:97], v192 offset:33792
	ds_read_b128 v[194:197], v192 offset:34816
	ds_read_b128 v[198:201], v192 offset:35840
	ds_read_b128 v[202:205], v192 offset:36864
	s_mov_b32 m0, s43
	ds_read_b128 v[206:209], v192 offset:37888
	global_load_lds_dwordx4 v168, s[100:101]
	s_mov_b32 m0, s44
	ds_read_b128 v[210:213], v192 offset:38912
	global_load_lds_dwordx4 v164, s[100:101]
	ds_read_b128 v[222:225], v192 offset:39936
	s_waitcnt vmcnt(8) lgkmcnt(0)
	s_barrier
	v_mfma_f32_16x16x32_bf16 v[150:153], v[66:69], v[90:93], v[150:153]
	v_mfma_f32_16x16x32_bf16 v[142:145], v[74:77], v[90:93], v[142:145]
	v_mfma_f32_16x16x32_bf16 v[134:137], v[66:69], v[194:197], v[134:137]
	v_mfma_f32_16x16x32_bf16 v[126:129], v[74:77], v[194:197], v[126:129]
	v_mfma_f32_16x16x32_bf16 v[118:121], v[66:69], v[202:205], v[118:121]
	v_mfma_f32_16x16x32_bf16 v[114:117], v[74:77], v[202:205], v[114:117]
	v_mfma_f32_16x16x32_bf16 v[110:113], v[66:69], v[210:213], v[110:113]
	v_mfma_f32_16x16x32_bf16 v[106:109], v[74:77], v[210:213], v[106:109]
	v_mfma_f32_16x16x32_bf16 v[150:153], v[70:73], v[94:97], v[150:153]
	v_mfma_f32_16x16x32_bf16 v[142:145], v[78:81], v[94:97], v[142:145]
	v_mfma_f32_16x16x32_bf16 v[134:137], v[70:73], v[198:201], v[134:137]
	v_mfma_f32_16x16x32_bf16 v[126:129], v[78:81], v[198:201], v[126:129]
	v_mfma_f32_16x16x32_bf16 v[118:121], v[70:73], v[206:209], v[118:121]
	v_mfma_f32_16x16x32_bf16 v[114:117], v[78:81], v[206:209], v[114:117]
	v_mfma_f32_16x16x32_bf16 v[110:113], v[70:73], v[222:225], v[110:113]
	v_mfma_f32_16x16x32_bf16 v[106:109], v[78:81], v[222:225], v[106:109]
	v_mfma_f32_16x16x32_bf16 v[158:161], v[82:85], v[90:93], v[158:161]
	v_mfma_f32_16x16x32_bf16 v[90:93], v[170:173], v[90:93], v[154:157]
	v_mfma_f32_16x16x32_bf16 v[154:157], v[184:187], v[94:97], v[90:93]
	v_mfma_f32_16x16x32_bf16 v[90:93], v[82:85], v[194:197], v[146:149]
	v_mfma_f32_16x16x32_bf16 v[146:149], v[86:89], v[198:201], v[90:93]
	v_mfma_f32_16x16x32_bf16 v[90:93], v[170:173], v[194:197], v[138:141]
	v_mfma_f32_16x16x32_bf16 v[138:141], v[184:187], v[198:201], v[90:93]
	v_mfma_f32_16x16x32_bf16 v[90:93], v[82:85], v[202:205], v[130:133]
	v_mfma_f32_16x16x32_bf16 v[130:133], v[86:89], v[206:209], v[90:93]
	v_mfma_f32_16x16x32_bf16 v[90:93], v[170:173], v[202:205], v[122:125]
	v_mfma_f32_16x16x32_bf16 v[122:125], v[184:187], v[206:209], v[90:93]
	v_mfma_f32_16x16x32_bf16 v[90:93], v[82:85], v[210:213], v[102:105]
	v_mfma_f32_16x16x32_bf16 v[102:105], v[86:89], v[222:225], v[90:93]
	v_mfma_f32_16x16x32_bf16 v[90:93], v[170:173], v[210:213], v[98:101]
	v_mfma_f32_16x16x32_bf16 v[158:161], v[86:89], v[94:97], v[158:161]
	v_mfma_f32_16x16x32_bf16 v[98:101], v[184:187], v[222:225], v[90:93]
	s_barrier
	ds_read_b128 v[90:93], v192 offset:49152
	s_add_i32 m0, s38, 0x17f80
	ds_read_b128 v[194:197], v192 offset:50176
	global_load_lds_dwordx4 v166, s[8:9] offset:128
	s_add_i32 m0, s38, 0x19f80
	ds_read_b128 v[198:201], v192 offset:51200
	global_load_lds_dwordx4 v162, s[8:9] offset:128
	s_add_i32 m0, s38, 0x1bf80
	ds_read_b128 v[202:205], v192 offset:52224
	global_load_lds_dwordx4 v166, s[52:53] offset:128
	s_add_i32 m0, s38, 0x1df80
	ds_read_b128 v[206:209], v192 offset:53248
	global_load_lds_dwordx4 v162, s[52:53] offset:128
	s_add_i32 m0, s46, 0xffffff80
	ds_read_b128 v[210:213], v192 offset:54272
	global_load_lds_dwordx4 v168, s[10:11] offset:128
	s_add_i32 m0, s47, 0xffffff80
	ds_read_b128 v[222:225], v192 offset:55296
	global_load_lds_dwordx4 v164, s[10:11] offset:128
	ds_read_b128 v[230:233], v192 offset:56320
	s_waitcnt vmcnt(8) lgkmcnt(0)
	s_barrier
	v_mfma_f32_16x16x32_bf16 v[58:61], v[66:69], v[90:93], v[58:61]
	v_mfma_f32_16x16x32_bf16 v[46:49], v[74:77], v[90:93], v[46:49]
	v_mfma_f32_16x16x32_bf16 v[38:41], v[66:69], v[198:201], v[38:41]
	v_mfma_f32_16x16x32_bf16 v[30:33], v[74:77], v[198:201], v[30:33]
	v_mfma_f32_16x16x32_bf16 v[22:25], v[66:69], v[206:209], v[22:25]
	v_mfma_f32_16x16x32_bf16 v[18:21], v[74:77], v[206:209], v[18:21]
	v_mfma_f32_16x16x32_bf16 v[8:11], v[66:69], v[222:225], v[8:11]
	v_mfma_f32_16x16x32_bf16 v[12:15], v[74:77], v[222:225], v[12:15]
	v_mfma_f32_16x16x32_bf16 v[58:61], v[70:73], v[194:197], v[58:61]
	v_mfma_f32_16x16x32_bf16 v[46:49], v[78:81], v[194:197], v[46:49]
	v_mfma_f32_16x16x32_bf16 v[38:41], v[70:73], v[202:205], v[38:41]
	v_mfma_f32_16x16x32_bf16 v[30:33], v[78:81], v[202:205], v[30:33]
	v_mfma_f32_16x16x32_bf16 v[22:25], v[70:73], v[210:213], v[22:25]
	v_mfma_f32_16x16x32_bf16 v[18:21], v[78:81], v[210:213], v[18:21]
	v_mfma_f32_16x16x32_bf16 v[8:11], v[70:73], v[230:233], v[8:11]
	v_mfma_f32_16x16x32_bf16 v[12:15], v[78:81], v[230:233], v[12:15]
	v_mfma_f32_16x16x32_bf16 v[54:57], v[82:85], v[90:93], v[54:57]
	v_mfma_f32_16x16x32_bf16 v[94:97], v[86:89], v[194:197], v[54:57]
	v_mfma_f32_16x16x32_bf16 v[54:57], v[170:173], v[90:93], v[62:65]
	v_mfma_f32_16x16x32_bf16 v[50:53], v[82:85], v[198:201], v[50:53]
	v_mfma_f32_16x16x32_bf16 v[42:45], v[170:173], v[198:201], v[42:45]
	v_mfma_f32_16x16x32_bf16 v[34:37], v[82:85], v[206:209], v[34:37]
	v_mfma_f32_16x16x32_bf16 v[26:29], v[170:173], v[206:209], v[26:29]
	v_mfma_f32_16x16x32_bf16 v[0:3], v[82:85], v[222:225], v[0:3]
	v_mfma_f32_16x16x32_bf16 v[4:7], v[170:173], v[222:225], v[4:7]
	v_mfma_f32_16x16x32_bf16 v[90:93], v[184:187], v[194:197], v[54:57]
	v_mfma_f32_16x16x32_bf16 v[50:53], v[86:89], v[202:205], v[50:53]
	v_mfma_f32_16x16x32_bf16 v[42:45], v[184:187], v[202:205], v[42:45]
	v_mfma_f32_16x16x32_bf16 v[34:37], v[86:89], v[210:213], v[34:37]
	v_mfma_f32_16x16x32_bf16 v[26:29], v[184:187], v[210:213], v[26:29]
	v_mfma_f32_16x16x32_bf16 v[0:3], v[86:89], v[230:233], v[0:3]
	v_mfma_f32_16x16x32_bf16 v[4:7], v[184:187], v[230:233], v[4:7]
	s_cmp_eq_u32 s51, 28
	s_cbranch_scc1 .Lxb_d0
	s_barrier
	s_add_i32 s51, s51, 2
	s_add_u32 s6, s6, 0x100
	s_addc_u32 s7, s7, 0
	s_add_u32 s30, s30, 0x100
	s_addc_u32 s31, s31, 0
	s_branch .LBB0_68
.Lxb_d0:
	s_add_i32 s51, s51, 2
	s_add_u32 s6, s6, 0x100
	s_addc_u32 s7, s7, 0
	s_add_u32 s30, s30, 0x100
	s_addc_u32 s31, s31, 0
	s_and_b64 vcc, exec, s[16:17]
	s_cbranch_vccz .LBB0_71
	s_barrier

.LBB0_108:
	s_add_u32 s16, s14, 0xfff80080
	s_addc_u32 s17, s15, -1
	s_cmp_eq_u32 s44, 28
	s_cselect_b32 s19, s9, s17
	s_cselect_b32 s18, s40, s16
	s_cselect_b32 s17, s7, s43
	s_cselect_b32 s16, s41, s42
	ds_read_b128 v[130:133], v170
	ds_read_b128 v[134:137], v170 offset:1024
	ds_read_b128 v[138:141], v170 offset:2048
	ds_read_b128 v[142:145], v170 offset:3072
	ds_read_b128 v[146:149], v171
	ds_read_b128 v[150:153], v171 offset:1024
	ds_read_b128 v[154:157], v171 offset:2048
	ds_read_b128 v[158:161], v171 offset:3072
	ds_read_b128 v[162:165], v208
	ds_read_b128 v[166:169], v208 offset:1024
	ds_read_b128 v[184:187], v208 offset:2048
	ds_read_b128 v[188:191], v208 offset:3072
	ds_read_b128 v[192:195], v208 offset:4096
	s_add_i32 m0, s25, 0xc000
	ds_read_b128 v[196:199], v208 offset:5120
	global_load_lds_dwordx4 v180, s[14:15]
	s_add_i32 m0, s25, 0xe000
	ds_read_b128 v[200:203], v208 offset:6144
	global_load_lds_dwordx4 v182, s[14:15]
	ds_read_b128 v[210:213], v208 offset:7168
	s_waitcnt vmcnt(8) lgkmcnt(0)
	s_barrier
	v_mfma_f32_16x16x32_bf16 v[126:129], v[130:133], v[162:165], v[126:129]
	v_mfma_f32_16x16x32_bf16 v[94:97], v[138:141], v[162:165], v[94:97]
	v_mfma_f32_16x16x32_bf16 v[122:125], v[130:133], v[184:187], v[122:125]
	v_mfma_f32_16x16x32_bf16 v[90:93], v[138:141], v[184:187], v[90:93]
	v_mfma_f32_16x16x32_bf16 v[118:121], v[130:133], v[192:195], v[118:121]
	v_mfma_f32_16x16x32_bf16 v[86:89], v[138:141], v[192:195], v[86:89]
	v_mfma_f32_16x16x32_bf16 v[114:117], v[130:133], v[200:203], v[114:117]
	v_mfma_f32_16x16x32_bf16 v[82:85], v[138:141], v[200:203], v[82:85]
	v_mfma_f32_16x16x32_bf16 v[126:129], v[134:137], v[166:169], v[126:129]
	v_mfma_f32_16x16x32_bf16 v[94:97], v[142:145], v[166:169], v[94:97]
	v_mfma_f32_16x16x32_bf16 v[122:125], v[134:137], v[188:191], v[122:125]
	v_mfma_f32_16x16x32_bf16 v[90:93], v[142:145], v[188:191], v[90:93]
	v_mfma_f32_16x16x32_bf16 v[118:121], v[134:137], v[196:199], v[118:121]
	v_mfma_f32_16x16x32_bf16 v[86:89], v[142:145], v[196:199], v[86:89]
	v_mfma_f32_16x16x32_bf16 v[114:117], v[134:137], v[210:213], v[114:117]
	v_mfma_f32_16x16x32_bf16 v[82:85], v[142:145], v[210:213], v[82:85]
	v_mfma_f32_16x16x32_bf16 v[66:69], v[146:149], v[162:165], v[66:69]
	v_mfma_f32_16x16x32_bf16 v[42:45], v[154:157], v[162:165], v[42:45]
	v_mfma_f32_16x16x32_bf16 v[58:61], v[146:149], v[184:187], v[58:61]
	v_mfma_f32_16x16x32_bf16 v[30:33], v[154:157], v[184:187], v[30:33]
	v_mfma_f32_16x16x32_bf16 v[54:57], v[146:149], v[192:195], v[54:57]
	v_mfma_f32_16x16x32_bf16 v[22:25], v[154:157], v[192:195], v[22:25]
	v_mfma_f32_16x16x32_bf16 v[50:53], v[146:149], v[200:203], v[50:53]
	v_mfma_f32_16x16x32_bf16 v[18:21], v[154:157], v[200:203], v[18:21]
	v_mfma_f32_16x16x32_bf16 v[66:69], v[150:153], v[166:169], v[66:69]
	v_mfma_f32_16x16x32_bf16 v[42:45], v[158:161], v[166:169], v[42:45]
	v_mfma_f32_16x16x32_bf16 v[58:61], v[150:153], v[188:191], v[58:61]
	v_mfma_f32_16x16x32_bf16 v[30:33], v[158:161], v[188:191], v[30:33]
	v_mfma_f32_16x16x32_bf16 v[54:57], v[150:153], v[196:199], v[54:57]
	v_mfma_f32_16x16x32_bf16 v[22:25], v[158:161], v[196:199], v[22:25]
	v_mfma_f32_16x16x32_bf16 v[50:53], v[150:153], v[210:213], v[50:53]
	v_mfma_f32_16x16x32_bf16 v[18:21], v[158:161], v[210:213], v[18:21]
	s_barrier
	ds_read_b128 v[162:165], v208 offset:16384
	s_add_i32 m0, s24, 0x10000
	ds_read_b128 v[166:169], v208 offset:17408
	global_load_lds_dwordx4 v178, s[16:17]
	s_add_i32 m0, s24, 0x12000
	s_add_u32 s46, s16, 0x80000
	s_addc_u32 s47, s17, 0
	ds_read_b128 v[184:187], v208 offset:18432
	global_load_lds_dwordx4 v176, s[16:17]
	s_add_i32 m0, s24, 0x14000
	ds_read_b128 v[188:191], v208 offset:19456
	global_load_lds_dwordx4 v178, s[46:47]
	s_add_i32 m0, s24, 0x16000
	ds_read_b128 v[192:195], v208 offset:20480
	global_load_lds_dwordx4 v176, s[46:47]
	s_mov_b32 m0, s25
	ds_read_b128 v[196:199], v208 offset:21504
	global_load_lds_dwordx4 v178, s[18:19]
	s_mov_b32 m0, s26
	ds_read_b128 v[200:203], v208 offset:22528
	global_load_lds_dwordx4 v176, s[18:19]
	ds_read_b128 v[210:213], v208 offset:23552
	s_waitcnt vmcnt(8) lgkmcnt(0)
	s_barrier
	v_mfma_f32_16x16x32_bf16 v[110:113], v[130:133], v[162:165], v[110:113]
	v_mfma_f32_16x16x32_bf16 v[78:81], v[138:141], v[162:165], v[78:81]
	v_mfma_f32_16x16x32_bf16 v[106:109], v[130:133], v[184:187], v[106:109]
	v_mfma_f32_16x16x32_bf16 v[74:77], v[138:141], v[184:187], v[74:77]
	v_mfma_f32_16x16x32_bf16 v[102:105], v[130:133], v[192:195], v[102:105]
	v_mfma_f32_16x16x32_bf16 v[70:73], v[138:141], v[192:195], v[70:73]
	v_mfma_f32_16x16x32_bf16 v[98:101], v[130:133], v[200:203], v[98:101]
	v_mfma_f32_16x16x32_bf16 v[62:65], v[138:141], v[200:203], v[62:65]
	v_mfma_f32_16x16x32_bf16 v[110:113], v[134:137], v[166:169], v[110:113]
	v_mfma_f32_16x16x32_bf16 v[78:81], v[142:145], v[166:169], v[78:81]
	v_mfma_f32_16x16x32_bf16 v[106:109], v[134:137], v[188:191], v[106:109]
	v_mfma_f32_16x16x32_bf16 v[74:77], v[142:145], v[188:191], v[74:77]
	v_mfma_f32_16x16x32_bf16 v[102:105], v[134:137], v[196:199], v[102:105]
	v_mfma_f32_16x16x32_bf16 v[70:73], v[142:145], v[196:199], v[70:73]
	v_mfma_f32_16x16x32_bf16 v[98:101], v[134:137], v[210:213], v[98:101]
	v_mfma_f32_16x16x32_bf16 v[62:65], v[142:145], v[210:213], v[62:65]
	v_mfma_f32_16x16x32_bf16 v[46:49], v[146:149], v[162:165], v[46:49]
	v_mfma_f32_16x16x32_bf16 v[12:15], v[154:157], v[162:165], v[12:15]
	v_mfma_f32_16x16x32_bf16 v[38:41], v[146:149], v[184:187], v[38:41]
	v_mfma_f32_16x16x32_bf16 v[8:11], v[154:157], v[184:187], v[8:11]
	v_mfma_f32_16x16x32_bf16 v[34:37], v[146:149], v[192:195], v[34:37]
	v_mfma_f32_16x16x32_bf16 v[4:7], v[154:157], v[192:195], v[4:7]
	v_mfma_f32_16x16x32_bf16 v[26:29], v[146:149], v[200:203], v[26:29]
	v_mfma_f32_16x16x32_bf16 v[0:3], v[154:157], v[200:203], v[0:3]
	v_mfma_f32_16x16x32_bf16 v[46:49], v[150:153], v[166:169], v[46:49]
	v_mfma_f32_16x16x32_bf16 v[12:15], v[158:161], v[166:169], v[12:15]
	v_mfma_f32_16x16x32_bf16 v[38:41], v[150:153], v[188:191], v[38:41]
	v_mfma_f32_16x16x32_bf16 v[8:11], v[158:161], v[188:191], v[8:11]
	v_mfma_f32_16x16x32_bf16 v[34:37], v[150:153], v[196:199], v[34:37]
	v_mfma_f32_16x16x32_bf16 v[4:7], v[158:161], v[196:199], v[4:7]
	v_mfma_f32_16x16x32_bf16 v[26:29], v[150:153], v[210:213], v[26:29]
	v_mfma_f32_16x16x32_bf16 v[0:3], v[158:161], v[210:213], v[0:3]
	s_barrier
	s_add_u32 s100, s18, 0x80000
	s_addc_u32 s101, s19, 0
	ds_read_b128 v[130:133], v172
	ds_read_b128 v[134:137], v172 offset:1024
	ds_read_b128 v[138:141], v172 offset:2048
	ds_read_b128 v[142:145], v172 offset:3072
	ds_read_b128 v[146:149], v173
	ds_read_b128 v[150:153], v173 offset:1024
	ds_read_b128 v[154:157], v173 offset:2048
	ds_read_b128 v[158:161], v173 offset:3072
	ds_read_b128 v[162:165], v208 offset:32768
	ds_read_b128 v[166:169], v208 offset:33792
	ds_read_b128 v[184:187], v208 offset:34816
	ds_read_b128 v[188:191], v208 offset:35840
	ds_read_b128 v[192:195], v208 offset:36864
	s_mov_b32 m0, s27
	ds_read_b128 v[196:199], v208 offset:37888
	global_load_lds_dwordx4 v178, s[100:101]
	s_mov_b32 m0, s28
	ds_read_b128 v[200:203], v208 offset:38912
	global_load_lds_dwordx4 v176, s[100:101]
	ds_read_b128 v[210:213], v208 offset:39936
	s_waitcnt vmcnt(8) lgkmcnt(0)
	s_barrier
	v_mfma_f32_16x16x32_bf16 v[126:129], v[130:133], v[162:165], v[126:129]
	v_mfma_f32_16x16x32_bf16 v[94:97], v[138:141], v[162:165], v[94:97]
	v_mfma_f32_16x16x32_bf16 v[122:125], v[130:133], v[184:187], v[122:125]
	v_mfma_f32_16x16x32_bf16 v[90:93], v[138:141], v[184:187], v[90:93]
	v_mfma_f32_16x16x32_bf16 v[118:121], v[130:133], v[192:195], v[118:121]
	v_mfma_f32_16x16x32_bf16 v[86:89], v[138:141], v[192:195], v[86:89]
	v_mfma_f32_16x16x32_bf16 v[114:117], v[130:133], v[200:203], v[114:117]
	v_mfma_f32_16x16x32_bf16 v[82:85], v[138:141], v[200:203], v[82:85]
	v_mfma_f32_16x16x32_bf16 v[126:129], v[134:137], v[166:169], v[126:129]
	v_mfma_f32_16x16x32_bf16 v[94:97], v[142:145], v[166:169], v[94:97]
	v_mfma_f32_16x16x32_bf16 v[122:125], v[134:137], v[188:191], v[122:125]
	v_mfma_f32_16x16x32_bf16 v[90:93], v[142:145], v[188:191], v[90:93]
	v_mfma_f32_16x16x32_bf16 v[118:121], v[134:137], v[196:199], v[118:121]
	v_mfma_f32_16x16x32_bf16 v[86:89], v[142:145], v[196:199], v[86:89]
	v_mfma_f32_16x16x32_bf16 v[114:117], v[134:137], v[210:213], v[114:117]
	v_mfma_f32_16x16x32_bf16 v[82:85], v[142:145], v[210:213], v[82:85]
	v_mfma_f32_16x16x32_bf16 v[66:69], v[146:149], v[162:165], v[66:69]
	v_mfma_f32_16x16x32_bf16 v[42:45], v[154:157], v[162:165], v[42:45]
	v_mfma_f32_16x16x32_bf16 v[58:61], v[146:149], v[184:187], v[58:61]
	v_mfma_f32_16x16x32_bf16 v[30:33], v[154:157], v[184:187], v[30:33]
	v_mfma_f32_16x16x32_bf16 v[54:57], v[146:149], v[192:195], v[54:57]
	v_mfma_f32_16x16x32_bf16 v[22:25], v[154:157], v[192:195], v[22:25]
	v_mfma_f32_16x16x32_bf16 v[50:53], v[146:149], v[200:203], v[50:53]
	v_mfma_f32_16x16x32_bf16 v[18:21], v[154:157], v[200:203], v[18:21]
	v_mfma_f32_16x16x32_bf16 v[66:69], v[150:153], v[166:169], v[66:69]
	v_mfma_f32_16x16x32_bf16 v[42:45], v[158:161], v[166:169], v[42:45]
	v_mfma_f32_16x16x32_bf16 v[58:61], v[150:153], v[188:191], v[58:61]
	v_mfma_f32_16x16x32_bf16 v[30:33], v[158:161], v[188:191], v[30:33]
	v_mfma_f32_16x16x32_bf16 v[54:57], v[150:153], v[196:199], v[54:57]
	v_mfma_f32_16x16x32_bf16 v[22:25], v[158:161], v[196:199], v[22:25]
	v_mfma_f32_16x16x32_bf16 v[50:53], v[150:153], v[210:213], v[50:53]
	v_mfma_f32_16x16x32_bf16 v[18:21], v[158:161], v[210:213], v[18:21]
	s_barrier
	ds_read_b128 v[162:165], v208 offset:49152
	s_add_i32 m0, s24, 0x17f80
	ds_read_b128 v[166:169], v208 offset:50176
	global_load_lds_dwordx4 v178, s[16:17] offset:128
	s_add_i32 m0, s24, 0x19f80
	ds_read_b128 v[184:187], v208 offset:51200
	global_load_lds_dwordx4 v176, s[16:17] offset:128
	s_add_i32 m0, s24, 0x1bf80
	ds_read_b128 v[188:191], v208 offset:52224
	global_load_lds_dwordx4 v178, s[46:47] offset:128
	s_add_i32 m0, s24, 0x1df80
	ds_read_b128 v[192:195], v208 offset:53248
	global_load_lds_dwordx4 v176, s[46:47] offset:128
	s_add_i32 m0, s35, 0xffffff80
	ds_read_b128 v[196:199], v208 offset:54272
	global_load_lds_dwordx4 v178, s[18:19] offset:128
	s_add_i32 m0, s36, 0xffffff80
	ds_read_b128 v[200:203], v208 offset:55296
	global_load_lds_dwordx4 v176, s[18:19] offset:128
	ds_read_b128 v[210:213], v208 offset:56320
	s_waitcnt vmcnt(8) lgkmcnt(0)
	s_barrier
	v_mfma_f32_16x16x32_bf16 v[110:113], v[130:133], v[162:165], v[110:113]
	v_mfma_f32_16x16x32_bf16 v[78:81], v[138:141], v[162:165], v[78:81]
	v_mfma_f32_16x16x32_bf16 v[106:109], v[130:133], v[184:187], v[106:109]
	v_mfma_f32_16x16x32_bf16 v[74:77], v[138:141], v[184:187], v[74:77]
	v_mfma_f32_16x16x32_bf16 v[102:105], v[130:133], v[192:195], v[102:105]
	v_mfma_f32_16x16x32_bf16 v[70:73], v[138:141], v[192:195], v[70:73]
	v_mfma_f32_16x16x32_bf16 v[98:101], v[130:133], v[200:203], v[98:101]
	v_mfma_f32_16x16x32_bf16 v[62:65], v[138:141], v[200:203], v[62:65]
	v_mfma_f32_16x16x32_bf16 v[110:113], v[134:137], v[166:169], v[110:113]
	v_mfma_f32_16x16x32_bf16 v[78:81], v[142:145], v[166:169], v[78:81]
	v_mfma_f32_16x16x32_bf16 v[106:109], v[134:137], v[188:191], v[106:109]
	v_mfma_f32_16x16x32_bf16 v[74:77], v[142:145], v[188:191], v[74:77]
	v_mfma_f32_16x16x32_bf16 v[102:105], v[134:137], v[196:199], v[102:105]
	v_mfma_f32_16x16x32_bf16 v[70:73], v[142:145], v[196:199], v[70:73]
	v_mfma_f32_16x16x32_bf16 v[98:101], v[134:137], v[210:213], v[98:101]
	v_mfma_f32_16x16x32_bf16 v[62:65], v[142:145], v[210:213], v[62:65]
	v_mfma_f32_16x16x32_bf16 v[46:49], v[146:149], v[162:165], v[46:49]
	v_mfma_f32_16x16x32_bf16 v[12:15], v[154:157], v[162:165], v[12:15]
	v_mfma_f32_16x16x32_bf16 v[38:41], v[146:149], v[184:187], v[38:41]
	v_mfma_f32_16x16x32_bf16 v[8:11], v[154:157], v[184:187], v[8:11]
	v_mfma_f32_16x16x32_bf16 v[34:37], v[146:149], v[192:195], v[34:37]
	v_mfma_f32_16x16x32_bf16 v[4:7], v[154:157], v[192:195], v[4:7]
	v_mfma_f32_16x16x32_bf16 v[26:29], v[146:149], v[200:203], v[26:29]
	v_mfma_f32_16x16x32_bf16 v[0:3], v[154:157], v[200:203], v[0:3]
	v_mfma_f32_16x16x32_bf16 v[46:49], v[150:153], v[166:169], v[46:49]
	v_mfma_f32_16x16x32_bf16 v[12:15], v[158:161], v[166:169], v[12:15]
	v_mfma_f32_16x16x32_bf16 v[38:41], v[150:153], v[188:191], v[38:41]
	v_mfma_f32_16x16x32_bf16 v[8:11], v[158:161], v[188:191], v[8:11]
	v_mfma_f32_16x16x32_bf16 v[34:37], v[150:153], v[196:199], v[34:37]
	v_mfma_f32_16x16x32_bf16 v[4:7], v[158:161], v[196:199], v[4:7]
	v_mfma_f32_16x16x32_bf16 v[26:29], v[150:153], v[210:213], v[26:29]
	v_mfma_f32_16x16x32_bf16 v[0:3], v[158:161], v[210:213], v[0:3]
	s_cmp_eq_u32 s44, 28
	s_cbranch_scc1 .Lxb_d1
	s_barrier
	s_add_i32 s44, s44, 2
	s_add_u32 s14, s14, 0x100
	s_addc_u32 s15, s15, 0
	s_add_u32 s42, s42, 0x100
	s_addc_u32 s43, s43, 0
	s_branch .LBB0_108
.Lxb_d1:
	s_add_i32 s44, s44, 2
	s_add_u32 s14, s14, 0x100
	s_addc_u32 s15, s15, 0
	s_add_u32 s42, s42, 0x100
	s_addc_u32 s43, s43, 0
	s_and_b64 vcc, exec, s[2:3]
	s_movk_i32 s44, 0x1000
	s_cbranch_vccz .LBB0_111
	s_barrier

.LBB0_552:
	s_add_u32 s8, s6, 0xfffe0080
	s_addc_u32 s9, s7, -1
	s_cmp_eq_u32 s46, 4
	s_cselect_b32 s25, s19, s9
	s_cselect_b32 s24, s42, s8
	s_cselect_b32 s9, s17, s45
	s_cselect_b32 s8, s43, s44
	ds_read_b128 v[58:61], v168
	ds_read_b128 v[70:73], v168 offset:1024
	ds_read_b128 v[74:77], v168 offset:2048
	ds_read_b128 v[86:89], v168 offset:3072
	ds_read_b128 v[122:125], v169
	ds_read_b128 v[126:129], v169 offset:1024
	ds_read_b128 v[154:157], v169 offset:2048
	ds_read_b128 v[176:179], v169 offset:3072
	ds_read_b128 v[186:189], v185
	ds_read_b128 v[190:193], v185 offset:1024
	ds_read_b128 v[194:197], v185 offset:2048
	ds_read_b128 v[198:201], v185 offset:3072
	ds_read_b128 v[202:205], v185 offset:4096
	s_add_i32 m0, s31, 0xc000
	ds_read_b128 v[206:209], v185 offset:5120
	global_load_lds_dwordx4 v164, s[6:7]
	s_add_i32 m0, s31, 0xe000
	ds_read_b128 v[210:213], v185 offset:6144
	global_load_lds_dwordx4 v166, s[6:7]
	ds_read_b128 v[230:233], v185 offset:7168
	s_waitcnt vmcnt(8) lgkmcnt(0)
	s_barrier
	v_mfma_f32_16x16x32_bf16 v[150:153], v[58:61], v[186:189], v[150:153]
	v_mfma_f32_16x16x32_bf16 v[146:149], v[74:77], v[186:189], v[146:149]
	v_mfma_f32_16x16x32_bf16 v[142:145], v[58:61], v[194:197], v[142:145]
	v_mfma_f32_16x16x32_bf16 v[138:141], v[74:77], v[194:197], v[138:141]
	v_mfma_f32_16x16x32_bf16 v[134:137], v[58:61], v[202:205], v[134:137]
	v_mfma_f32_16x16x32_bf16 v[130:133], v[74:77], v[202:205], v[130:133]
	v_mfma_f32_16x16x32_bf16 v[118:121], v[58:61], v[210:213], v[118:121]
	v_mfma_f32_16x16x32_bf16 v[114:117], v[74:77], v[210:213], v[114:117]
	v_mfma_f32_16x16x32_bf16 v[150:153], v[70:73], v[190:193], v[150:153]
	v_mfma_f32_16x16x32_bf16 v[146:149], v[86:89], v[190:193], v[146:149]
	v_mfma_f32_16x16x32_bf16 v[142:145], v[70:73], v[198:201], v[142:145]
	v_mfma_f32_16x16x32_bf16 v[138:141], v[86:89], v[198:201], v[138:141]
	v_mfma_f32_16x16x32_bf16 v[134:137], v[70:73], v[206:209], v[134:137]
	v_mfma_f32_16x16x32_bf16 v[130:133], v[86:89], v[206:209], v[130:133]
	v_mfma_f32_16x16x32_bf16 v[118:121], v[70:73], v[230:233], v[118:121]
	v_mfma_f32_16x16x32_bf16 v[114:117], v[86:89], v[230:233], v[114:117]
	v_mfma_f32_16x16x32_bf16 v[66:69], v[122:125], v[186:189], v[66:69]
	v_mfma_f32_16x16x32_bf16 v[62:65], v[154:157], v[186:189], v[62:65]
	v_mfma_f32_16x16x32_bf16 v[54:57], v[122:125], v[194:197], v[54:57]
	v_mfma_f32_16x16x32_bf16 v[50:53], v[154:157], v[194:197], v[50:53]
	v_mfma_f32_16x16x32_bf16 v[46:49], v[122:125], v[202:205], v[46:49]
	v_mfma_f32_16x16x32_bf16 v[42:45], v[154:157], v[202:205], v[42:45]
	v_mfma_f32_16x16x32_bf16 v[38:41], v[122:125], v[210:213], v[38:41]
	v_mfma_f32_16x16x32_bf16 v[34:37], v[154:157], v[210:213], v[34:37]
	v_mfma_f32_16x16x32_bf16 v[66:69], v[126:129], v[190:193], v[66:69]
	v_mfma_f32_16x16x32_bf16 v[62:65], v[176:179], v[190:193], v[62:65]
	v_mfma_f32_16x16x32_bf16 v[54:57], v[126:129], v[198:201], v[54:57]
	v_mfma_f32_16x16x32_bf16 v[50:53], v[176:179], v[198:201], v[50:53]
	v_mfma_f32_16x16x32_bf16 v[46:49], v[126:129], v[206:209], v[46:49]
	v_mfma_f32_16x16x32_bf16 v[42:45], v[176:179], v[206:209], v[42:45]
	v_mfma_f32_16x16x32_bf16 v[38:41], v[126:129], v[230:233], v[38:41]
	v_mfma_f32_16x16x32_bf16 v[34:37], v[176:179], v[230:233], v[34:37]
	s_barrier
	ds_read_b128 v[186:189], v185 offset:16384
	s_add_i32 m0, s30, 0x10000
	ds_read_b128 v[190:193], v185 offset:17408
	global_load_lds_dwordx4 v16, s[8:9]
	s_add_i32 m0, s30, 0x12000
	s_add_u32 s48, s8, 0x20000
	s_addc_u32 s49, s9, 0
	ds_read_b128 v[194:197], v185 offset:18432
	global_load_lds_dwordx4 v158, s[8:9]
	s_add_i32 m0, s30, 0x14000
	ds_read_b128 v[198:201], v185 offset:19456
	global_load_lds_dwordx4 v16, s[48:49]
	s_add_i32 m0, s30, 0x16000
	ds_read_b128 v[202:205], v185 offset:20480
	global_load_lds_dwordx4 v158, s[48:49]
	s_mov_b32 m0, s31
	ds_read_b128 v[206:209], v185 offset:21504
	global_load_lds_dwordx4 v162, s[24:25]
	s_mov_b32 m0, s34
	ds_read_b128 v[210:213], v185 offset:22528
	global_load_lds_dwordx4 v160, s[24:25]
	ds_read_b128 v[230:233], v185 offset:23552
	s_waitcnt vmcnt(8) lgkmcnt(0)
	s_barrier
	v_mfma_f32_16x16x32_bf16 v[110:113], v[58:61], v[186:189], v[110:113]
	v_mfma_f32_16x16x32_bf16 v[106:109], v[74:77], v[186:189], v[106:109]
	v_mfma_f32_16x16x32_bf16 v[102:105], v[58:61], v[194:197], v[102:105]
	v_mfma_f32_16x16x32_bf16 v[98:101], v[74:77], v[194:197], v[98:101]
	v_mfma_f32_16x16x32_bf16 v[94:97], v[58:61], v[202:205], v[94:97]
	v_mfma_f32_16x16x32_bf16 v[90:93], v[74:77], v[202:205], v[90:93]
	v_mfma_f32_16x16x32_bf16 v[58:61], v[58:61], v[210:213], v[82:85]
	v_mfma_f32_16x16x32_bf16 v[110:113], v[70:73], v[190:193], v[110:113]
	v_mfma_f32_16x16x32_bf16 v[106:109], v[86:89], v[190:193], v[106:109]
	v_mfma_f32_16x16x32_bf16 v[102:105], v[70:73], v[198:201], v[102:105]
	v_mfma_f32_16x16x32_bf16 v[98:101], v[86:89], v[198:201], v[98:101]
	v_mfma_f32_16x16x32_bf16 v[94:97], v[70:73], v[206:209], v[94:97]
	v_mfma_f32_16x16x32_bf16 v[90:93], v[86:89], v[206:209], v[90:93]
	v_mfma_f32_16x16x32_bf16 v[58:61], v[70:73], v[230:233], v[58:61]
	v_mfma_f32_16x16x32_bf16 v[70:73], v[74:77], v[210:213], v[78:81]
	v_mfma_f32_16x16x32_bf16 v[70:73], v[86:89], v[230:233], v[70:73]
	v_mfma_f32_16x16x32_bf16 v[30:33], v[122:125], v[186:189], v[30:33]
	v_mfma_f32_16x16x32_bf16 v[26:29], v[154:157], v[186:189], v[26:29]
	v_mfma_f32_16x16x32_bf16 v[22:25], v[122:125], v[194:197], v[22:25]
	v_mfma_f32_16x16x32_bf16 v[18:21], v[154:157], v[194:197], v[18:21]
	v_mfma_f32_16x16x32_bf16 v[12:15], v[122:125], v[202:205], v[12:15]
	v_mfma_f32_16x16x32_bf16 v[8:11], v[154:157], v[202:205], v[8:11]
	v_mfma_f32_16x16x32_bf16 v[4:7], v[122:125], v[210:213], v[4:7]
	v_mfma_f32_16x16x32_bf16 v[0:3], v[154:157], v[210:213], v[0:3]
	v_mfma_f32_16x16x32_bf16 v[30:33], v[126:129], v[190:193], v[30:33]
	v_mfma_f32_16x16x32_bf16 v[26:29], v[176:179], v[190:193], v[26:29]
	v_mfma_f32_16x16x32_bf16 v[22:25], v[126:129], v[198:201], v[22:25]
	v_mfma_f32_16x16x32_bf16 v[18:21], v[176:179], v[198:201], v[18:21]
	v_mfma_f32_16x16x32_bf16 v[12:15], v[126:129], v[206:209], v[12:15]
	v_mfma_f32_16x16x32_bf16 v[8:11], v[176:179], v[206:209], v[8:11]
	v_mfma_f32_16x16x32_bf16 v[4:7], v[126:129], v[230:233], v[4:7]
	v_mfma_f32_16x16x32_bf16 v[0:3], v[176:179], v[230:233], v[0:3]
	s_barrier
	s_add_u32 s100, s24, 0x20000
	s_addc_u32 s101, s25, 0
	ds_read_b128 v[74:77], v170
	ds_read_b128 v[78:81], v170 offset:1024
	ds_read_b128 v[86:89], v170 offset:2048
	ds_read_b128 v[122:125], v170 offset:3072
	ds_read_b128 v[126:129], v171
	ds_read_b128 v[154:157], v171 offset:1024
	ds_read_b128 v[176:179], v171 offset:2048
	ds_read_b128 v[186:189], v171 offset:3072
	ds_read_b128 v[82:85], v185 offset:32768
	ds_read_b128 v[190:193], v185 offset:33792
	ds_read_b128 v[194:197], v185 offset:34816
	ds_read_b128 v[198:201], v185 offset:35840
	ds_read_b128 v[202:205], v185 offset:36864
	s_mov_b32 m0, s35
	ds_read_b128 v[206:209], v185 offset:37888
	global_load_lds_dwordx4 v162, s[100:101]
	s_mov_b32 m0, s36
	ds_read_b128 v[210:213], v185 offset:38912
	global_load_lds_dwordx4 v160, s[100:101]
	ds_read_b128 v[230:233], v185 offset:39936
	s_waitcnt vmcnt(8) lgkmcnt(0)
	s_barrier
	v_mfma_f32_16x16x32_bf16 v[150:153], v[74:77], v[82:85], v[150:153]
	v_mfma_f32_16x16x32_bf16 v[146:149], v[86:89], v[82:85], v[146:149]
	v_mfma_f32_16x16x32_bf16 v[142:145], v[74:77], v[194:197], v[142:145]
	v_mfma_f32_16x16x32_bf16 v[138:141], v[86:89], v[194:197], v[138:141]
	v_mfma_f32_16x16x32_bf16 v[134:137], v[74:77], v[202:205], v[134:137]
	v_mfma_f32_16x16x32_bf16 v[130:133], v[86:89], v[202:205], v[130:133]
	v_mfma_f32_16x16x32_bf16 v[118:121], v[74:77], v[210:213], v[118:121]
	v_mfma_f32_16x16x32_bf16 v[114:117], v[86:89], v[210:213], v[114:117]
	v_mfma_f32_16x16x32_bf16 v[150:153], v[78:81], v[190:193], v[150:153]
	v_mfma_f32_16x16x32_bf16 v[146:149], v[122:125], v[190:193], v[146:149]
	v_mfma_f32_16x16x32_bf16 v[142:145], v[78:81], v[198:201], v[142:145]
	v_mfma_f32_16x16x32_bf16 v[138:141], v[122:125], v[198:201], v[138:141]
	v_mfma_f32_16x16x32_bf16 v[134:137], v[78:81], v[206:209], v[134:137]
	v_mfma_f32_16x16x32_bf16 v[130:133], v[122:125], v[206:209], v[130:133]
	v_mfma_f32_16x16x32_bf16 v[118:121], v[78:81], v[230:233], v[118:121]
	v_mfma_f32_16x16x32_bf16 v[114:117], v[122:125], v[230:233], v[114:117]
	v_mfma_f32_16x16x32_bf16 v[66:69], v[126:129], v[82:85], v[66:69]
	v_mfma_f32_16x16x32_bf16 v[62:65], v[176:179], v[82:85], v[62:65]
	v_mfma_f32_16x16x32_bf16 v[54:57], v[126:129], v[194:197], v[54:57]
	v_mfma_f32_16x16x32_bf16 v[50:53], v[176:179], v[194:197], v[50:53]
	v_mfma_f32_16x16x32_bf16 v[46:49], v[126:129], v[202:205], v[46:49]
	v_mfma_f32_16x16x32_bf16 v[42:45], v[176:179], v[202:205], v[42:45]
	v_mfma_f32_16x16x32_bf16 v[38:41], v[126:129], v[210:213], v[38:41]
	v_mfma_f32_16x16x32_bf16 v[34:37], v[176:179], v[210:213], v[34:37]
	v_mfma_f32_16x16x32_bf16 v[66:69], v[154:157], v[190:193], v[66:69]
	v_mfma_f32_16x16x32_bf16 v[62:65], v[186:189], v[190:193], v[62:65]
	v_mfma_f32_16x16x32_bf16 v[54:57], v[154:157], v[198:201], v[54:57]
	v_mfma_f32_16x16x32_bf16 v[50:53], v[186:189], v[198:201], v[50:53]
	v_mfma_f32_16x16x32_bf16 v[46:49], v[154:157], v[206:209], v[46:49]
	v_mfma_f32_16x16x32_bf16 v[42:45], v[186:189], v[206:209], v[42:45]
	v_mfma_f32_16x16x32_bf16 v[38:41], v[154:157], v[230:233], v[38:41]
	v_mfma_f32_16x16x32_bf16 v[34:37], v[186:189], v[230:233], v[34:37]
	s_barrier
	ds_read_b128 v[190:193], v185 offset:49152
	s_add_i32 m0, s30, 0x17f80
	ds_read_b128 v[194:197], v185 offset:50176
	global_load_lds_dwordx4 v16, s[8:9] offset:128
	s_add_i32 m0, s30, 0x19f80
	ds_read_b128 v[198:201], v185 offset:51200
	global_load_lds_dwordx4 v158, s[8:9] offset:128
	s_add_i32 m0, s30, 0x1bf80
	ds_read_b128 v[202:205], v185 offset:52224
	global_load_lds_dwordx4 v16, s[48:49] offset:128
	s_add_i32 m0, s30, 0x1df80
	ds_read_b128 v[206:209], v185 offset:53248
	global_load_lds_dwordx4 v158, s[48:49] offset:128
	s_add_i32 m0, s38, 0xffffff80
	ds_read_b128 v[210:213], v185 offset:54272
	global_load_lds_dwordx4 v162, s[24:25] offset:128
	s_add_i32 m0, s39, 0xffffff80
	ds_read_b128 v[230:233], v185 offset:55296
	global_load_lds_dwordx4 v160, s[24:25] offset:128
	ds_read_b128 v[234:237], v185 offset:56320
	s_waitcnt vmcnt(8) lgkmcnt(0)
	s_barrier
	v_mfma_f32_16x16x32_bf16 v[82:85], v[74:77], v[190:193], v[110:113]
	v_mfma_f32_16x16x32_bf16 v[110:113], v[78:81], v[194:197], v[82:85]
	v_mfma_f32_16x16x32_bf16 v[82:85], v[86:89], v[190:193], v[106:109]
	v_mfma_f32_16x16x32_bf16 v[106:109], v[122:125], v[194:197], v[82:85]
	v_mfma_f32_16x16x32_bf16 v[82:85], v[74:77], v[198:201], v[102:105]
	v_mfma_f32_16x16x32_bf16 v[102:105], v[78:81], v[202:205], v[82:85]
	v_mfma_f32_16x16x32_bf16 v[82:85], v[86:89], v[198:201], v[98:101]
	v_mfma_f32_16x16x32_bf16 v[98:101], v[122:125], v[202:205], v[82:85]
	v_mfma_f32_16x16x32_bf16 v[82:85], v[74:77], v[206:209], v[94:97]
	v_mfma_f32_16x16x32_bf16 v[94:97], v[78:81], v[210:213], v[82:85]
	v_mfma_f32_16x16x32_bf16 v[82:85], v[86:89], v[206:209], v[90:93]
	v_mfma_f32_16x16x32_bf16 v[58:61], v[74:77], v[230:233], v[58:61]
	v_mfma_f32_16x16x32_bf16 v[90:93], v[122:125], v[210:213], v[82:85]
	v_mfma_f32_16x16x32_bf16 v[82:85], v[78:81], v[234:237], v[58:61]
	v_mfma_f32_16x16x32_bf16 v[58:61], v[86:89], v[230:233], v[70:73]
	v_mfma_f32_16x16x32_bf16 v[78:81], v[122:125], v[234:237], v[58:61]
	v_mfma_f32_16x16x32_bf16 v[30:33], v[126:129], v[190:193], v[30:33]
	v_mfma_f32_16x16x32_bf16 v[26:29], v[176:179], v[190:193], v[26:29]
	v_mfma_f32_16x16x32_bf16 v[22:25], v[126:129], v[198:201], v[22:25]
	v_mfma_f32_16x16x32_bf16 v[18:21], v[176:179], v[198:201], v[18:21]
	v_mfma_f32_16x16x32_bf16 v[12:15], v[126:129], v[206:209], v[12:15]
	v_mfma_f32_16x16x32_bf16 v[8:11], v[176:179], v[206:209], v[8:11]
	v_mfma_f32_16x16x32_bf16 v[4:7], v[126:129], v[230:233], v[4:7]
	v_mfma_f32_16x16x32_bf16 v[0:3], v[176:179], v[230:233], v[0:3]
	v_mfma_f32_16x16x32_bf16 v[30:33], v[154:157], v[194:197], v[30:33]
	v_mfma_f32_16x16x32_bf16 v[26:29], v[186:189], v[194:197], v[26:29]
	v_mfma_f32_16x16x32_bf16 v[22:25], v[154:157], v[202:205], v[22:25]
	v_mfma_f32_16x16x32_bf16 v[18:21], v[186:189], v[202:205], v[18:21]
	v_mfma_f32_16x16x32_bf16 v[12:15], v[154:157], v[210:213], v[12:15]
	v_mfma_f32_16x16x32_bf16 v[8:11], v[186:189], v[210:213], v[8:11]
	v_mfma_f32_16x16x32_bf16 v[4:7], v[154:157], v[234:237], v[4:7]
	v_mfma_f32_16x16x32_bf16 v[0:3], v[186:189], v[234:237], v[0:3]
	s_cmp_eq_u32 s46, 4
	s_cbranch_scc1 .Lxb_d3
	s_barrier
	s_add_i32 s46, s46, 2
	s_add_u32 s6, s6, 0x100
	s_addc_u32 s7, s7, 0
	s_add_u32 s44, s44, 0x100
	s_addc_u32 s45, s45, 0
	s_branch .LBB0_552
.Lxb_d3:
	s_add_i32 s46, s46, 2
	s_add_u32 s6, s6, 0x100
	s_addc_u32 s7, s7, 0
	s_add_u32 s44, s44, 0x100
	s_addc_u32 s45, s45, 0
	s_and_b64 vcc, exec, s[14:15]
	s_cbranch_vccz .LBB0_555
	s_barrier

.LBB0_1018:
	s_add_u32 s26, s24, 0xfff80080
	s_addc_u32 s27, s25, -1
	s_cmp_eq_u32 s62, 28
	s_cselect_b32 s29, s19, s27
	s_cselect_b32 s28, s31, s26
	s_cselect_b32 s27, s17, s61
	s_cselect_b32 s26, s55, s60
	ds_read_b128 v[144:147], v168
	ds_read_b128 v[148:151], v168 offset:1024
	ds_read_b128 v[152:155], v168 offset:2048
	ds_read_b128 v[156:159], v168 offset:3072
	ds_read_b128 v[160:163], v169
	ds_read_b128 v[176:179], v169 offset:1024
	ds_read_b128 v[180:183], v169 offset:2048
	ds_read_b128 v[184:187], v169 offset:3072
	ds_read_b128 v[188:191], v167
	ds_read_b128 v[192:195], v167 offset:1024
	ds_read_b128 v[196:199], v167 offset:2048
	ds_read_b128 v[200:203], v167 offset:3072
	ds_read_b128 v[204:207], v167 offset:4096
	s_add_i32 m0, s39, 0xc000
	ds_read_b128 v[208:211], v167 offset:5120
	global_load_lds_dwordx4 v140, s[24:25]
	s_add_i32 m0, s39, 0xe000
	ds_read_b128 v[212:215], v167 offset:6144
	global_load_lds_dwordx4 v142, s[24:25]
	ds_read_b128 v[230:233], v167 offset:7168
	s_waitcnt vmcnt(8) lgkmcnt(0)
	s_barrier
	v_mfma_f32_16x16x32_bf16 v[66:69], v[144:147], v[188:191], v[66:69]
	v_mfma_f32_16x16x32_bf16 v[62:65], v[152:155], v[188:191], v[62:65]
	v_mfma_f32_16x16x32_bf16 v[58:61], v[144:147], v[196:199], v[58:61]
	v_mfma_f32_16x16x32_bf16 v[54:57], v[152:155], v[196:199], v[54:57]
	v_mfma_f32_16x16x32_bf16 v[46:49], v[144:147], v[204:207], v[46:49]
	v_mfma_f32_16x16x32_bf16 v[42:45], v[152:155], v[204:207], v[42:45]
	v_mfma_f32_16x16x32_bf16 v[38:41], v[144:147], v[212:215], v[38:41]
	v_mfma_f32_16x16x32_bf16 v[34:37], v[152:155], v[212:215], v[34:37]
	v_mfma_f32_16x16x32_bf16 v[66:69], v[148:151], v[192:195], v[66:69]
	v_mfma_f32_16x16x32_bf16 v[62:65], v[156:159], v[192:195], v[62:65]
	v_mfma_f32_16x16x32_bf16 v[58:61], v[148:151], v[200:203], v[58:61]
	v_mfma_f32_16x16x32_bf16 v[54:57], v[156:159], v[200:203], v[54:57]
	v_mfma_f32_16x16x32_bf16 v[46:49], v[148:151], v[208:211], v[46:49]
	v_mfma_f32_16x16x32_bf16 v[42:45], v[156:159], v[208:211], v[42:45]
	v_mfma_f32_16x16x32_bf16 v[38:41], v[148:151], v[230:233], v[38:41]
	v_mfma_f32_16x16x32_bf16 v[34:37], v[156:159], v[230:233], v[34:37]
	v_mfma_f32_16x16x32_bf16 v[126:129], v[160:163], v[188:191], v[126:129]
	v_mfma_f32_16x16x32_bf16 v[122:125], v[180:183], v[188:191], v[122:125]
	v_mfma_f32_16x16x32_bf16 v[118:121], v[160:163], v[196:199], v[118:121]
	v_mfma_f32_16x16x32_bf16 v[114:117], v[180:183], v[196:199], v[114:117]
	v_mfma_f32_16x16x32_bf16 v[110:113], v[160:163], v[204:207], v[110:113]
	v_mfma_f32_16x16x32_bf16 v[106:109], v[180:183], v[204:207], v[106:109]
	v_mfma_f32_16x16x32_bf16 v[102:105], v[160:163], v[212:215], v[102:105]
	v_mfma_f32_16x16x32_bf16 v[98:101], v[180:183], v[212:215], v[98:101]
	v_mfma_f32_16x16x32_bf16 v[126:129], v[176:179], v[192:195], v[126:129]
	v_mfma_f32_16x16x32_bf16 v[122:125], v[184:187], v[192:195], v[122:125]
	v_mfma_f32_16x16x32_bf16 v[118:121], v[176:179], v[200:203], v[118:121]
	v_mfma_f32_16x16x32_bf16 v[114:117], v[184:187], v[200:203], v[114:117]
	v_mfma_f32_16x16x32_bf16 v[110:113], v[176:179], v[208:211], v[110:113]
	v_mfma_f32_16x16x32_bf16 v[106:109], v[184:187], v[208:211], v[106:109]
	v_mfma_f32_16x16x32_bf16 v[102:105], v[176:179], v[230:233], v[102:105]
	v_mfma_f32_16x16x32_bf16 v[98:101], v[184:187], v[230:233], v[98:101]
	s_barrier
	ds_read_b128 v[188:191], v167 offset:16384
	s_add_i32 m0, s38, 0x10000
	ds_read_b128 v[192:195], v167 offset:17408
	global_load_lds_dwordx4 v132, s[26:27]
	s_add_i32 m0, s38, 0x12000
	s_add_u32 s64, s26, 0x80000
	s_addc_u32 s65, s27, 0
	ds_read_b128 v[196:199], v167 offset:18432
	global_load_lds_dwordx4 v136, s[26:27]
	s_add_i32 m0, s38, 0x14000
	ds_read_b128 v[200:203], v167 offset:19456
	global_load_lds_dwordx4 v132, s[64:65]
	s_add_i32 m0, s38, 0x16000
	ds_read_b128 v[204:207], v167 offset:20480
	global_load_lds_dwordx4 v136, s[64:65]
	s_mov_b32 m0, s39
	ds_read_b128 v[208:211], v167 offset:21504
	global_load_lds_dwordx4 v130, s[28:29]
	s_mov_b32 m0, s40
	ds_read_b128 v[212:215], v167 offset:22528
	global_load_lds_dwordx4 v134, s[28:29]
	ds_read_b128 v[230:233], v167 offset:23552
	s_waitcnt vmcnt(8) lgkmcnt(0)
	s_barrier
	v_mfma_f32_16x16x32_bf16 v[30:33], v[144:147], v[188:191], v[30:33]
	v_mfma_f32_16x16x32_bf16 v[26:29], v[152:155], v[188:191], v[26:29]
	v_mfma_f32_16x16x32_bf16 v[22:25], v[144:147], v[196:199], v[22:25]
	v_mfma_f32_16x16x32_bf16 v[18:21], v[152:155], v[196:199], v[18:21]
	v_mfma_f32_16x16x32_bf16 v[12:15], v[144:147], v[204:207], v[12:15]
	v_mfma_f32_16x16x32_bf16 v[8:11], v[152:155], v[204:207], v[8:11]
	v_mfma_f32_16x16x32_bf16 v[4:7], v[144:147], v[212:215], v[4:7]
	v_mfma_f32_16x16x32_bf16 v[0:3], v[152:155], v[212:215], v[0:3]
	v_mfma_f32_16x16x32_bf16 v[30:33], v[148:151], v[192:195], v[30:33]
	v_mfma_f32_16x16x32_bf16 v[26:29], v[156:159], v[192:195], v[26:29]
	v_mfma_f32_16x16x32_bf16 v[22:25], v[148:151], v[200:203], v[22:25]
	v_mfma_f32_16x16x32_bf16 v[18:21], v[156:159], v[200:203], v[18:21]
	v_mfma_f32_16x16x32_bf16 v[12:15], v[148:151], v[208:211], v[12:15]
	v_mfma_f32_16x16x32_bf16 v[8:11], v[156:159], v[208:211], v[8:11]
	v_mfma_f32_16x16x32_bf16 v[4:7], v[148:151], v[230:233], v[4:7]
	v_mfma_f32_16x16x32_bf16 v[0:3], v[156:159], v[230:233], v[0:3]
	v_mfma_f32_16x16x32_bf16 v[94:97], v[160:163], v[188:191], v[94:97]
	v_mfma_f32_16x16x32_bf16 v[90:93], v[180:183], v[188:191], v[90:93]
	v_mfma_f32_16x16x32_bf16 v[86:89], v[160:163], v[196:199], v[86:89]
	v_mfma_f32_16x16x32_bf16 v[82:85], v[180:183], v[196:199], v[82:85]
	v_mfma_f32_16x16x32_bf16 v[78:81], v[160:163], v[204:207], v[78:81]
	v_mfma_f32_16x16x32_bf16 v[74:77], v[180:183], v[204:207], v[74:77]
	v_mfma_f32_16x16x32_bf16 v[70:73], v[160:163], v[212:215], v[70:73]
	v_mfma_f32_16x16x32_bf16 v[50:53], v[180:183], v[212:215], v[50:53]
	v_mfma_f32_16x16x32_bf16 v[94:97], v[176:179], v[192:195], v[94:97]
	v_mfma_f32_16x16x32_bf16 v[90:93], v[184:187], v[192:195], v[90:93]
	v_mfma_f32_16x16x32_bf16 v[86:89], v[176:179], v[200:203], v[86:89]
	v_mfma_f32_16x16x32_bf16 v[82:85], v[184:187], v[200:203], v[82:85]
	v_mfma_f32_16x16x32_bf16 v[78:81], v[176:179], v[208:211], v[78:81]
	v_mfma_f32_16x16x32_bf16 v[74:77], v[184:187], v[208:211], v[74:77]
	v_mfma_f32_16x16x32_bf16 v[70:73], v[176:179], v[230:233], v[70:73]
	v_mfma_f32_16x16x32_bf16 v[50:53], v[184:187], v[230:233], v[50:53]
	s_barrier
	s_add_u32 s100, s28, 0x80000
	s_addc_u32 s101, s29, 0
	ds_read_b128 v[144:147], v170
	ds_read_b128 v[148:151], v170 offset:1024
	ds_read_b128 v[152:155], v170 offset:2048
	ds_read_b128 v[156:159], v170 offset:3072
	ds_read_b128 v[160:163], v171
	ds_read_b128 v[176:179], v171 offset:1024
	ds_read_b128 v[180:183], v171 offset:2048
	ds_read_b128 v[184:187], v171 offset:3072
	ds_read_b128 v[188:191], v167 offset:32768
	ds_read_b128 v[192:195], v167 offset:33792
	ds_read_b128 v[196:199], v167 offset:34816
	ds_read_b128 v[200:203], v167 offset:35840
	ds_read_b128 v[204:207], v167 offset:36864
	s_mov_b32 m0, s41
	ds_read_b128 v[208:211], v167 offset:37888
	global_load_lds_dwordx4 v130, s[100:101]
	s_mov_b32 m0, s42
	ds_read_b128 v[212:215], v167 offset:38912
	global_load_lds_dwordx4 v134, s[100:101]
	ds_read_b128 v[230:233], v167 offset:39936
	s_waitcnt vmcnt(8) lgkmcnt(0)
	s_barrier
	v_mfma_f32_16x16x32_bf16 v[66:69], v[144:147], v[188:191], v[66:69]
	v_mfma_f32_16x16x32_bf16 v[62:65], v[152:155], v[188:191], v[62:65]
	v_mfma_f32_16x16x32_bf16 v[58:61], v[144:147], v[196:199], v[58:61]
	v_mfma_f32_16x16x32_bf16 v[54:57], v[152:155], v[196:199], v[54:57]
	v_mfma_f32_16x16x32_bf16 v[46:49], v[144:147], v[204:207], v[46:49]
	v_mfma_f32_16x16x32_bf16 v[42:45], v[152:155], v[204:207], v[42:45]
	v_mfma_f32_16x16x32_bf16 v[38:41], v[144:147], v[212:215], v[38:41]
	v_mfma_f32_16x16x32_bf16 v[34:37], v[152:155], v[212:215], v[34:37]
	v_mfma_f32_16x16x32_bf16 v[66:69], v[148:151], v[192:195], v[66:69]
	v_mfma_f32_16x16x32_bf16 v[62:65], v[156:159], v[192:195], v[62:65]
	v_mfma_f32_16x16x32_bf16 v[58:61], v[148:151], v[200:203], v[58:61]
	v_mfma_f32_16x16x32_bf16 v[54:57], v[156:159], v[200:203], v[54:57]
	v_mfma_f32_16x16x32_bf16 v[46:49], v[148:151], v[208:211], v[46:49]
	v_mfma_f32_16x16x32_bf16 v[42:45], v[156:159], v[208:211], v[42:45]
	v_mfma_f32_16x16x32_bf16 v[38:41], v[148:151], v[230:233], v[38:41]
	v_mfma_f32_16x16x32_bf16 v[34:37], v[156:159], v[230:233], v[34:37]
	v_mfma_f32_16x16x32_bf16 v[126:129], v[160:163], v[188:191], v[126:129]
	v_mfma_f32_16x16x32_bf16 v[122:125], v[180:183], v[188:191], v[122:125]
	v_mfma_f32_16x16x32_bf16 v[118:121], v[160:163], v[196:199], v[118:121]
	v_mfma_f32_16x16x32_bf16 v[114:117], v[180:183], v[196:199], v[114:117]
	v_mfma_f32_16x16x32_bf16 v[110:113], v[160:163], v[204:207], v[110:113]
	v_mfma_f32_16x16x32_bf16 v[106:109], v[180:183], v[204:207], v[106:109]
	v_mfma_f32_16x16x32_bf16 v[102:105], v[160:163], v[212:215], v[102:105]
	v_mfma_f32_16x16x32_bf16 v[98:101], v[180:183], v[212:215], v[98:101]
	v_mfma_f32_16x16x32_bf16 v[126:129], v[176:179], v[192:195], v[126:129]
	v_mfma_f32_16x16x32_bf16 v[122:125], v[184:187], v[192:195], v[122:125]
	v_mfma_f32_16x16x32_bf16 v[118:121], v[176:179], v[200:203], v[118:121]
	v_mfma_f32_16x16x32_bf16 v[114:117], v[184:187], v[200:203], v[114:117]
	v_mfma_f32_16x16x32_bf16 v[110:113], v[176:179], v[208:211], v[110:113]
	v_mfma_f32_16x16x32_bf16 v[106:109], v[184:187], v[208:211], v[106:109]
	v_mfma_f32_16x16x32_bf16 v[102:105], v[176:179], v[230:233], v[102:105]
	v_mfma_f32_16x16x32_bf16 v[98:101], v[184:187], v[230:233], v[98:101]
	s_barrier
	ds_read_b128 v[188:191], v167 offset:49152
	s_add_i32 m0, s38, 0x17f80
	ds_read_b128 v[192:195], v167 offset:50176
	global_load_lds_dwordx4 v132, s[26:27] offset:128
	s_add_i32 m0, s38, 0x19f80
	ds_read_b128 v[196:199], v167 offset:51200
	global_load_lds_dwordx4 v136, s[26:27] offset:128
	s_add_i32 m0, s38, 0x1bf80
	ds_read_b128 v[200:203], v167 offset:52224
	global_load_lds_dwordx4 v132, s[64:65] offset:128
	s_add_i32 m0, s38, 0x1df80
	ds_read_b128 v[204:207], v167 offset:53248
	global_load_lds_dwordx4 v136, s[64:65] offset:128
	s_add_i32 m0, s46, 0xffffff80
	ds_read_b128 v[208:211], v167 offset:54272
	global_load_lds_dwordx4 v130, s[28:29] offset:128
	s_add_i32 m0, s47, 0xffffff80
	ds_read_b128 v[212:215], v167 offset:55296
	global_load_lds_dwordx4 v134, s[28:29] offset:128
	ds_read_b128 v[230:233], v167 offset:56320
	s_waitcnt vmcnt(8) lgkmcnt(0)
	s_barrier
	v_mfma_f32_16x16x32_bf16 v[30:33], v[144:147], v[188:191], v[30:33]
	v_mfma_f32_16x16x32_bf16 v[26:29], v[152:155], v[188:191], v[26:29]
	v_mfma_f32_16x16x32_bf16 v[22:25], v[144:147], v[196:199], v[22:25]
	v_mfma_f32_16x16x32_bf16 v[18:21], v[152:155], v[196:199], v[18:21]
	v_mfma_f32_16x16x32_bf16 v[12:15], v[144:147], v[204:207], v[12:15]
	v_mfma_f32_16x16x32_bf16 v[8:11], v[152:155], v[204:207], v[8:11]
	v_mfma_f32_16x16x32_bf16 v[4:7], v[144:147], v[212:215], v[4:7]
	v_mfma_f32_16x16x32_bf16 v[0:3], v[152:155], v[212:215], v[0:3]
	v_mfma_f32_16x16x32_bf16 v[30:33], v[148:151], v[192:195], v[30:33]
	v_mfma_f32_16x16x32_bf16 v[26:29], v[156:159], v[192:195], v[26:29]
	v_mfma_f32_16x16x32_bf16 v[22:25], v[148:151], v[200:203], v[22:25]
	v_mfma_f32_16x16x32_bf16 v[18:21], v[156:159], v[200:203], v[18:21]
	v_mfma_f32_16x16x32_bf16 v[12:15], v[148:151], v[208:211], v[12:15]
	v_mfma_f32_16x16x32_bf16 v[8:11], v[156:159], v[208:211], v[8:11]
	v_mfma_f32_16x16x32_bf16 v[4:7], v[148:151], v[230:233], v[4:7]
	v_mfma_f32_16x16x32_bf16 v[0:3], v[156:159], v[230:233], v[0:3]
	v_mfma_f32_16x16x32_bf16 v[94:97], v[160:163], v[188:191], v[94:97]
	v_mfma_f32_16x16x32_bf16 v[90:93], v[180:183], v[188:191], v[90:93]
	v_mfma_f32_16x16x32_bf16 v[86:89], v[160:163], v[196:199], v[86:89]
	v_mfma_f32_16x16x32_bf16 v[82:85], v[180:183], v[196:199], v[82:85]
	v_mfma_f32_16x16x32_bf16 v[78:81], v[160:163], v[204:207], v[78:81]
	v_mfma_f32_16x16x32_bf16 v[74:77], v[180:183], v[204:207], v[74:77]
	v_mfma_f32_16x16x32_bf16 v[70:73], v[160:163], v[212:215], v[70:73]
	v_mfma_f32_16x16x32_bf16 v[50:53], v[180:183], v[212:215], v[50:53]
	v_mfma_f32_16x16x32_bf16 v[94:97], v[176:179], v[192:195], v[94:97]
	v_mfma_f32_16x16x32_bf16 v[90:93], v[184:187], v[192:195], v[90:93]
	v_mfma_f32_16x16x32_bf16 v[86:89], v[176:179], v[200:203], v[86:89]
	v_mfma_f32_16x16x32_bf16 v[82:85], v[184:187], v[200:203], v[82:85]
	v_mfma_f32_16x16x32_bf16 v[78:81], v[176:179], v[208:211], v[78:81]
	v_mfma_f32_16x16x32_bf16 v[74:77], v[184:187], v[208:211], v[74:77]
	v_mfma_f32_16x16x32_bf16 v[70:73], v[176:179], v[230:233], v[70:73]
	v_mfma_f32_16x16x32_bf16 v[50:53], v[184:187], v[230:233], v[50:53]
	s_cmp_eq_u32 s62, 28
	s_cbranch_scc1 .Lxb_d4
	s_barrier
	s_add_i32 s62, s62, 2
	s_add_u32 s24, s24, 0x100
	s_addc_u32 s25, s25, 0
	s_add_u32 s60, s60, 0x100
	s_addc_u32 s61, s61, 0
	s_branch .LBB0_1018
.Lxb_d4:
	s_add_i32 s62, s62, 2
	s_add_u32 s24, s24, 0x100
	s_addc_u32 s25, s25, 0
	s_add_u32 s60, s60, 0x100
	s_addc_u32 s61, s61, 0
	s_and_b64 vcc, exec, s[8:9]
	s_cbranch_vccz .LBB0_1021
	s_barrier
